# diff-attn M segment opens with 4 PV MFMAs on a V-fragment block prefetched at the end of the previous M segment (covers K-fragment LDS latency); rest as previous version
# baseline (speedup 1.0000x reference)
; __device__ __forceinline__ float max3f(float a, float b, float c) { return __builtin_fmaxf(__builtin_fmaxf(a, b), c); }
; __device__ __forceinline__ void rowmax_adjust(f32x16& p0, f32x16& p1, float& m2, f32x16& negm, float& alpha, const bool first) {
;     constexpr float THR2 = THR * 1.4426950408889634f;
;     float pmax = max3f(p0[0], p0[1], p0[2]);
; #pragma unroll
;     for (int r = 3; r < 15; r += 2) pmax = max3f(pmax, p0[r], p0[r + 1]);
;     pmax = max3f(pmax, p0[15], p1[0]);
; #pragma unroll
;     for (int r = 1; r < 15; r += 2) pmax = max3f(pmax, p1[r], p1[r + 1]);
;     pmax = fmaxf(pmax, p1[15]);
;     { auto rr = __builtin_amdgcn_permlane32_swap(__float_as_uint(pmax), __float_as_uint(pmax), false, false);
;       pmax = fmaxf(__uint_as_float(rr[0]), __uint_as_float(rr[1])); }
;     if (!first && __builtin_expect(__all(pmax <= THR2), 1)) { alpha = 1.f; }
.LBB0_1150:
	s_add_i32 s95, s94, -3
	s_mul_i32 s0, s95, 0xab
	s_bfe_u32 s0, s0, 0x70009
	s_mul_i32 s0, s0, 3
	s_sub_i32 s0, s95, s0
	s_and_b32 s0, s0, 0xff
	s_mulk_i32 s0, 0x2400
	v_add_u32_e32 v84, s0, v218
	s_add_i32 s1, s51, 0xc000
	s_and_b32 s96, s1, 0xc000
	v_add_u32_e32 v236, s96, v217
	s_cmp_eq_u32 s51, 0
	s_cselect_b64 s[72:73], -1, 0
	ds_read_b128 v[80:83], v84
	ds_read_b128 v[224:227], v84 offset:4608
	ds_read_b128 v[220:223], v84 offset:32
	ds_read_b128 v[228:231], v84 offset:4640
	ds_read_b128 v[192:195], v84 offset:64
	ds_read_b128 v[196:199], v84 offset:4672
	ds_read_b128 v[184:187], v84 offset:96
	ds_read_b128 v[188:191], v84 offset:4704
	s_and_b64 vcc, exec, s[72:73]
	s_cbranch_vccnz .Ld3_ae_skip0
	v_mfma_f32_32x32x16_bf16 v[48:63], v[180:183], v[164:167], v[48:63]
	v_mfma_f32_32x32x16_bf16 v[48:63], v[176:179], v[160:163], v[48:63]
	v_mfma_f32_32x32x16_bf16 v[48:63], v[172:175], v[156:159], v[48:63]
	v_mfma_f32_32x32x16_bf16 v[48:63], v[168:171], v[152:155], v[48:63]
.Ld3_ae_skip0:
	s_waitcnt lgkmcnt(7)
	v_mfma_f32_32x32x16_bf16 v[96:111], v[80:83], v[112:115], v[64:79]
	s_waitcnt lgkmcnt(6)
	v_mfma_f32_32x32x16_bf16 v[80:95], v[224:227], v[112:115], v[64:79]
	s_waitcnt lgkmcnt(5)
	v_mfma_f32_32x32x16_bf16 v[96:111], v[220:223], v[116:119], v[96:111]
	s_waitcnt lgkmcnt(4)
	v_mfma_f32_32x32x16_bf16 v[80:95], v[228:231], v[116:119], v[80:95]
	s_waitcnt lgkmcnt(0)
	ds_read_b64_tr_b16 v[220:221], v236 offset:0x200
	ds_read_b64_tr_b16 v[222:223], v236 offset:0xa00
	ds_read_b64_tr_b16 v[224:225], v236 offset:0x1200
	ds_read_b64_tr_b16 v[226:227], v236 offset:0x1a00
	ds_read_b64_tr_b16 v[228:229], v236 offset:0x2200
	ds_read_b64_tr_b16 v[230:231], v236 offset:0x2a00
	ds_read_b64_tr_b16 v[232:233], v236 offset:0x3200
	ds_read_b64_tr_b16 v[234:235], v236 offset:0x3a00
	ds_read_b64_tr_b16 v[164:165], v236 offset:0x400
	ds_read_b64_tr_b16 v[166:167], v236 offset:0xc00
	ds_read_b64_tr_b16 v[160:161], v236 offset:0x1400
	ds_read_b64_tr_b16 v[162:163], v236 offset:0x1c00
	ds_read_b64_tr_b16 v[156:157], v236 offset:0x2400
	ds_read_b64_tr_b16 v[158:159], v236 offset:0x2c00
	ds_read_b64_tr_b16 v[152:153], v236 offset:0x3400
	ds_read_b64_tr_b16 v[154:155], v236 offset:0x3c00
	v_mfma_f32_32x32x16_bf16 v[96:111], v[192:195], v[120:123], v[96:111]
	v_mfma_f32_32x32x16_bf16 v[80:95], v[196:199], v[120:123], v[80:95]
	v_mfma_f32_32x32x16_bf16 v[96:111], v[184:187], v[124:127], v[96:111]
	v_mfma_f32_32x32x16_bf16 v[80:95], v[188:191], v[124:127], v[80:95]
	ds_read_b64_tr_b16 v[184:185], v236 offset:0x600
	ds_read_b64_tr_b16 v[186:187], v236 offset:0xe00
	ds_read_b64_tr_b16 v[188:189], v236 offset:0x1600
	ds_read_b64_tr_b16 v[190:191], v236 offset:0x1e00
	ds_read_b64_tr_b16 v[192:193], v236 offset:0x2600
	ds_read_b64_tr_b16 v[194:195], v236 offset:0x2e00
	ds_read_b64_tr_b16 v[196:197], v236 offset:0x3600
	ds_read_b64_tr_b16 v[198:199], v236 offset:0x3e00
	s_and_b64 vcc, exec, s[72:73]
	s_cbranch_vccnz .Ld3_ae_nopv
	s_waitcnt lgkmcnt(15)
	v_mfma_f32_32x32x16_bf16 v[32:47], v[180:183], v[220:223], v[32:47]
	v_mfma_f32_32x32x16_bf16 v[32:47], v[176:179], v[224:227], v[32:47]
	v_mfma_f32_32x32x16_bf16 v[32:47], v[172:175], v[228:231], v[32:47]
	v_mfma_f32_32x32x16_bf16 v[32:47], v[168:171], v[232:235], v[32:47]
	s_waitcnt lgkmcnt(0)
	v_mfma_f32_32x32x16_bf16 v[0:15], v[180:183], v[184:187], v[0:15]
	v_mfma_f32_32x32x16_bf16 v[0:15], v[176:179], v[188:191], v[0:15]
	v_mfma_f32_32x32x16_bf16 v[0:15], v[172:175], v[192:195], v[0:15]
	v_mfma_f32_32x32x16_bf16 v[0:15], v[168:171], v[196:199], v[0:15]
	v_mfma_f32_32x32x16_bf16 v[16:31], v[180:183], v[164:167], v[16:31]
	v_mfma_f32_32x32x16_bf16 v[16:31], v[176:179], v[160:163], v[16:31]
	v_mfma_f32_32x32x16_bf16 v[16:31], v[172:175], v[156:159], v[16:31]
	v_mfma_f32_32x32x16_bf16 v[16:31], v[168:171], v[152:155], v[16:31]
.Ld3_ae_nopv:
	s_waitcnt lgkmcnt(0)
	s_and_b32 s0, s51, 0xc000
	v_add_u32_e32 v240, s0, v217
	ds_read_b64_tr_b16 v[164:165], v240 offset:0
	ds_read_b64_tr_b16 v[166:167], v240 offset:0x800
	ds_read_b64_tr_b16 v[160:161], v240 offset:0x1000
	ds_read_b64_tr_b16 v[162:163], v240 offset:0x1800
	ds_read_b64_tr_b16 v[156:157], v240 offset:0x2000
	ds_read_b64_tr_b16 v[158:159], v240 offset:0x2800
	ds_read_b64_tr_b16 v[152:153], v240 offset:0x3000
	ds_read_b64_tr_b16 v[154:155], v240 offset:0x3800
	s_mov_b64 s[0:1], s[72:73]
	s_barrier
	v_max3_f32 v168, v96, v97, v98
	v_max3_f32 v169, v81, v82, v83
	v_max3_f32 v168, v168, v99, v100
	v_max3_f32 v169, v169, v84, v85
	v_max3_f32 v168, v168, v101, v102
	v_max3_f32 v169, v169, v86, v87
	v_max3_f32 v168, v168, v103, v104
	v_max3_f32 v169, v169, v88, v89
	v_max3_f32 v168, v168, v105, v106
	v_max3_f32 v169, v169, v90, v91
	v_max3_f32 v168, v168, v107, v108
	v_max3_f32 v169, v169, v92, v93
	v_max3_f32 v168, v168, v109, v110
	v_max3_f32 v169, v169, v94, v95
	v_max3_f32 v168, v168, v111, v80
	v_max_f32_e32 v168, v168, v169
	v_mov_b32_e32 v169, v168
	s_nop 1
	v_permlane32_swap_b32_e32 v168, v169
	v_max_f32_e32 v168, v168, v169
	v_cmp_ge_f32_e32 vcc, s83, v168
	v_mov_b32_e32 v184, 1.0
	s_cmp_lg_u64 s[0:1], 0
	s_cbranch_scc1 .Lvt0_first
	s_cmp_lg_u64 vcc, exec
	s_cbranch_scc1 .Lvt0_rare
	s_branch .LBB0_1162

; __device__ __forceinline__ float max3f(float a, float b, float c) { return __builtin_fmaxf(__builtin_fmaxf(a, b), c); }
; __device__ __forceinline__ void rowmax_adjust(f32x16& p0, f32x16& p1, float& m2, f32x16& negm, float& alpha, const bool first) {
;     constexpr float THR2 = THR * 1.4426950408889634f;
;     float pmax = max3f(p0[0], p0[1], p0[2]);
; #pragma unroll
;     for (int r = 3; r < 15; r += 2) pmax = max3f(pmax, p0[r], p0[r + 1]);
;     pmax = max3f(pmax, p0[15], p1[0]);
; #pragma unroll
;     for (int r = 1; r < 15; r += 2) pmax = max3f(pmax, p1[r], p1[r + 1]);
;     pmax = fmaxf(pmax, p1[15]);
;     { auto rr = __builtin_amdgcn_permlane32_swap(__float_as_uint(pmax), __float_as_uint(pmax), false, false);
;       pmax = fmaxf(__uint_as_float(rr[0]), __uint_as_float(rr[1])); }
;     if (!first && __builtin_expect(__all(pmax <= THR2), 1)) { alpha = 1.f; }
.LBB0_1164:
	s_min_u32 s0, s95, 0x7f
	s_lshl_b32 s0, s0, 16
	s_add_i32 s16, s0, 0x40000
	s_add_u32 s0, s58, s16
	s_addc_u32 s1, s59, 0
	global_load_dwordx4 v[132:135], v200, s[0:1]
	global_load_dwordx4 v[128:131], v202, s[0:1]
	v_lshl_add_u64 v[80:81], v[204:205], 0, s[16:17]
	global_load_dwordx4 v[136:139], v[80:81], off
	s_waitcnt lgkmcnt(0)
	s_barrier
	s_or_b32 s0, s95, 1
	s_and_b32 s1, s0, 0xff
	s_mulk_i32 s1, 0xab
	s_bfe_u32 s1, s1, 0x70009
	s_mul_i32 s1, s1, 3
	s_sub_i32 s0, s0, s1
	s_and_b32 s0, s0, 0xff
	s_mulk_i32 s0, 0x2400
	v_add_u32_e32 v84, s0, v218
	s_and_b32 s0, s51, 0x8000
	v_add_u32_e32 v187, s0, v217
	ds_read_b128 v[80:83], v84
	ds_read_b128 v[192:195], v84 offset:4608
	ds_read_b128 v[188:191], v84 offset:32
	ds_read_b128 v[196:199], v84 offset:4640
	ds_read_b128 v[220:223], v84 offset:64
	ds_read_b128 v[228:231], v84 offset:4672
	ds_read_b128 v[224:227], v84 offset:96
	ds_read_b128 v[232:235], v84 offset:4704
	v_mfma_f32_32x32x16_bf16 v[48:63], v[180:183], v[164:167], v[48:63]
	v_mfma_f32_32x32x16_bf16 v[48:63], v[176:179], v[160:163], v[48:63]
	v_mfma_f32_32x32x16_bf16 v[48:63], v[172:175], v[156:159], v[48:63]
	v_mfma_f32_32x32x16_bf16 v[48:63], v[168:171], v[152:155], v[48:63]
	s_waitcnt lgkmcnt(7)
	v_mfma_f32_32x32x16_bf16 v[96:111], v[80:83], v[112:115], v[64:79]
	s_waitcnt lgkmcnt(6)
	v_mfma_f32_32x32x16_bf16 v[80:95], v[192:195], v[112:115], v[64:79]
	s_waitcnt lgkmcnt(5)
	v_mfma_f32_32x32x16_bf16 v[96:111], v[188:191], v[116:119], v[96:111]
	s_waitcnt lgkmcnt(4)
	v_mfma_f32_32x32x16_bf16 v[80:95], v[196:199], v[116:119], v[80:95]
	s_waitcnt lgkmcnt(0)
	ds_read_b64_tr_b16 v[188:189], v187 offset:0x200
	ds_read_b64_tr_b16 v[190:191], v187 offset:0xa00
	ds_read_b64_tr_b16 v[192:193], v187 offset:0x1200
	ds_read_b64_tr_b16 v[194:195], v187 offset:0x1a00
	ds_read_b64_tr_b16 v[196:197], v187 offset:0x2200
	ds_read_b64_tr_b16 v[198:199], v187 offset:0x2a00
	ds_read_b64_tr_b16 v[236:237], v187 offset:0x3200
	ds_read_b64_tr_b16 v[238:239], v187 offset:0x3a00
	ds_read_b64_tr_b16 v[164:165], v187 offset:0x400
	ds_read_b64_tr_b16 v[166:167], v187 offset:0xc00
	ds_read_b64_tr_b16 v[160:161], v187 offset:0x1400
	ds_read_b64_tr_b16 v[162:163], v187 offset:0x1c00
	ds_read_b64_tr_b16 v[156:157], v187 offset:0x2400
	ds_read_b64_tr_b16 v[158:159], v187 offset:0x2c00
	ds_read_b64_tr_b16 v[152:153], v187 offset:0x3400
	ds_read_b64_tr_b16 v[154:155], v187 offset:0x3c00
	v_mfma_f32_32x32x16_bf16 v[96:111], v[220:223], v[120:123], v[96:111]
	v_mfma_f32_32x32x16_bf16 v[80:95], v[228:231], v[120:123], v[80:95]
	v_mfma_f32_32x32x16_bf16 v[96:111], v[224:227], v[124:127], v[96:111]
	v_mfma_f32_32x32x16_bf16 v[80:95], v[232:235], v[124:127], v[80:95]
	ds_read_b64_tr_b16 v[220:221], v187 offset:0x600
	ds_read_b64_tr_b16 v[222:223], v187 offset:0xe00
	ds_read_b64_tr_b16 v[224:225], v187 offset:0x1600
	ds_read_b64_tr_b16 v[226:227], v187 offset:0x1e00
	ds_read_b64_tr_b16 v[228:229], v187 offset:0x2600
	ds_read_b64_tr_b16 v[230:231], v187 offset:0x2e00
	ds_read_b64_tr_b16 v[232:233], v187 offset:0x3600
	ds_read_b64_tr_b16 v[234:235], v187 offset:0x3e00
	s_waitcnt lgkmcnt(15)
	v_mfma_f32_32x32x16_bf16 v[32:47], v[180:183], v[188:191], v[32:47]
	v_mfma_f32_32x32x16_bf16 v[32:47], v[176:179], v[192:195], v[32:47]
	v_mfma_f32_32x32x16_bf16 v[32:47], v[172:175], v[196:199], v[32:47]
	v_mfma_f32_32x32x16_bf16 v[32:47], v[168:171], v[236:239], v[32:47]
	s_waitcnt lgkmcnt(0)
	v_mfma_f32_32x32x16_bf16 v[0:15], v[180:183], v[220:223], v[0:15]
	v_mfma_f32_32x32x16_bf16 v[0:15], v[176:179], v[224:227], v[0:15]
	v_mfma_f32_32x32x16_bf16 v[0:15], v[172:175], v[228:231], v[0:15]
	v_mfma_f32_32x32x16_bf16 v[0:15], v[168:171], v[232:235], v[0:15]
	v_mfma_f32_32x32x16_bf16 v[16:31], v[180:183], v[164:167], v[16:31]
	v_mfma_f32_32x32x16_bf16 v[16:31], v[176:179], v[160:163], v[16:31]
	v_mfma_f32_32x32x16_bf16 v[16:31], v[172:175], v[156:159], v[16:31]
	v_mfma_f32_32x32x16_bf16 v[16:31], v[168:171], v[152:155], v[16:31]
	s_add_i32 s0, s51, 0x4000
	s_and_b32 s0, s0, 0xc000
	v_add_u32_e32 v240, s0, v217
	ds_read_b64_tr_b16 v[164:165], v240 offset:0
	ds_read_b64_tr_b16 v[166:167], v240 offset:0x800
	ds_read_b64_tr_b16 v[160:161], v240 offset:0x1000
	ds_read_b64_tr_b16 v[162:163], v240 offset:0x1800
	ds_read_b64_tr_b16 v[156:157], v240 offset:0x2000
	ds_read_b64_tr_b16 v[158:159], v240 offset:0x2800
	ds_read_b64_tr_b16 v[152:153], v240 offset:0x3000
	ds_read_b64_tr_b16 v[154:155], v240 offset:0x3800
	s_barrier
	v_max3_f32 v168, v96, v97, v98
	v_max3_f32 v169, v81, v82, v83
	v_max3_f32 v168, v168, v99, v100
	v_max3_f32 v169, v169, v84, v85
	v_max3_f32 v168, v168, v101, v102
	v_max3_f32 v169, v169, v86, v87
	v_max3_f32 v168, v168, v103, v104
	v_max3_f32 v169, v169, v88, v89
	v_max3_f32 v168, v168, v105, v106
	v_max3_f32 v169, v169, v90, v91
	v_max3_f32 v168, v168, v107, v108
	v_max3_f32 v169, v169, v92, v93
	v_max3_f32 v168, v168, v109, v110
	v_max3_f32 v169, v169, v94, v95
	v_max3_f32 v168, v168, v111, v80
	v_max_f32_e32 v168, v168, v169
	v_mov_b32_e32 v169, v168
	s_nop 1
	v_permlane32_swap_b32_e32 v168, v169
	v_max_f32_e32 v168, v168, v169
	v_cmp_ge_f32_e32 vcc, s83, v168
	v_mov_b32_e32 v187, 1.0
	s_cmp_eq_u64 vcc, exec
	s_cbranch_scc1 .LBB0_1169
	s_branch .LBB0_1171

; __device__ __forceinline__ float max3f(float a, float b, float c) { return __builtin_fmaxf(__builtin_fmaxf(a, b), c); }
; __device__ __forceinline__ void rowmax_adjust(f32x16& p0, f32x16& p1, float& m2, f32x16& negm, float& alpha, const bool first) {
;     constexpr float THR2 = THR * 1.4426950408889634f;
;     float pmax = max3f(p0[0], p0[1], p0[2]);
; #pragma unroll
;     for (int r = 3; r < 15; r += 2) pmax = max3f(pmax, p0[r], p0[r + 1]);
;     pmax = max3f(pmax, p0[15], p1[0]);
; #pragma unroll
;     for (int r = 1; r < 15; r += 2) pmax = max3f(pmax, p1[r], p1[r + 1]);
;     pmax = fmaxf(pmax, p1[15]);
;     { auto rr = __builtin_amdgcn_permlane32_swap(__float_as_uint(pmax), __float_as_uint(pmax), false, false);
;       pmax = fmaxf(__uint_as_float(rr[0]), __uint_as_float(rr[1])); }
;     if (!first && __builtin_expect(__all(pmax <= THR2), 1)) { alpha = 1.f; }
.LBB0_1181:
	s_add_i32 s64, s7, -3
	s_mul_i32 s0, s64, 0xab
	s_bfe_u32 s0, s0, 0x70009
	s_mul_i32 s0, s0, 3
	s_sub_i32 s0, s64, s0
	s_and_b32 s0, s0, 0xff
	s_mulk_i32 s0, 0x2400
	v_add_u32_e32 v84, s0, v218
	s_add_i32 s1, s51, 0xc000
	s_and_b32 s65, s1, 0xc000
	v_add_u32_e32 v236, s65, v217
	s_cmp_eq_u32 s51, 0
	s_cselect_b64 s[60:61], -1, 0
	ds_read_b128 v[80:83], v84
	ds_read_b128 v[224:227], v84 offset:4608
	ds_read_b128 v[220:223], v84 offset:32
	ds_read_b128 v[228:231], v84 offset:4640
	ds_read_b128 v[192:195], v84 offset:64
	ds_read_b128 v[196:199], v84 offset:4672
	ds_read_b128 v[184:187], v84 offset:96
	ds_read_b128 v[188:191], v84 offset:4704
	s_and_b64 vcc, exec, s[60:61]
	s_cbranch_vccnz .Ld3_be_skip0
	v_mfma_f32_32x32x16_bf16 v[48:63], v[180:183], v[164:167], v[48:63]
	v_mfma_f32_32x32x16_bf16 v[48:63], v[176:179], v[160:163], v[48:63]
	v_mfma_f32_32x32x16_bf16 v[48:63], v[172:175], v[156:159], v[48:63]
	v_mfma_f32_32x32x16_bf16 v[48:63], v[168:171], v[152:155], v[48:63]
.Ld3_be_skip0:
	s_waitcnt lgkmcnt(7)
	v_mfma_f32_32x32x16_bf16 v[96:111], v[80:83], v[112:115], v[64:79]
	s_waitcnt lgkmcnt(6)
	v_mfma_f32_32x32x16_bf16 v[80:95], v[224:227], v[112:115], v[64:79]
	s_waitcnt lgkmcnt(5)
	v_mfma_f32_32x32x16_bf16 v[96:111], v[220:223], v[116:119], v[96:111]
	s_waitcnt lgkmcnt(4)
	v_mfma_f32_32x32x16_bf16 v[80:95], v[228:231], v[116:119], v[80:95]
	s_waitcnt lgkmcnt(0)
	ds_read_b64_tr_b16 v[220:221], v236 offset:0x200
	ds_read_b64_tr_b16 v[222:223], v236 offset:0xa00
	ds_read_b64_tr_b16 v[224:225], v236 offset:0x1200
	ds_read_b64_tr_b16 v[226:227], v236 offset:0x1a00
	ds_read_b64_tr_b16 v[228:229], v236 offset:0x2200
	ds_read_b64_tr_b16 v[230:231], v236 offset:0x2a00
	ds_read_b64_tr_b16 v[232:233], v236 offset:0x3200
	ds_read_b64_tr_b16 v[234:235], v236 offset:0x3a00
	ds_read_b64_tr_b16 v[164:165], v236 offset:0x400
	ds_read_b64_tr_b16 v[166:167], v236 offset:0xc00
	ds_read_b64_tr_b16 v[160:161], v236 offset:0x1400
	ds_read_b64_tr_b16 v[162:163], v236 offset:0x1c00
	ds_read_b64_tr_b16 v[156:157], v236 offset:0x2400
	ds_read_b64_tr_b16 v[158:159], v236 offset:0x2c00
	ds_read_b64_tr_b16 v[152:153], v236 offset:0x3400
	ds_read_b64_tr_b16 v[154:155], v236 offset:0x3c00
	v_mfma_f32_32x32x16_bf16 v[96:111], v[192:195], v[120:123], v[96:111]
	v_mfma_f32_32x32x16_bf16 v[80:95], v[196:199], v[120:123], v[80:95]
	v_mfma_f32_32x32x16_bf16 v[96:111], v[184:187], v[124:127], v[96:111]
	v_mfma_f32_32x32x16_bf16 v[80:95], v[188:191], v[124:127], v[80:95]
	ds_read_b64_tr_b16 v[184:185], v236 offset:0x600
	ds_read_b64_tr_b16 v[186:187], v236 offset:0xe00
	ds_read_b64_tr_b16 v[188:189], v236 offset:0x1600
	ds_read_b64_tr_b16 v[190:191], v236 offset:0x1e00
	ds_read_b64_tr_b16 v[192:193], v236 offset:0x2600
	ds_read_b64_tr_b16 v[194:195], v236 offset:0x2e00
	ds_read_b64_tr_b16 v[196:197], v236 offset:0x3600
	ds_read_b64_tr_b16 v[198:199], v236 offset:0x3e00
	s_and_b64 vcc, exec, s[60:61]
	s_cbranch_vccnz .Ld3_be_nopv
	s_waitcnt lgkmcnt(15)
	v_mfma_f32_32x32x16_bf16 v[32:47], v[180:183], v[220:223], v[32:47]
	v_mfma_f32_32x32x16_bf16 v[32:47], v[176:179], v[224:227], v[32:47]
	v_mfma_f32_32x32x16_bf16 v[32:47], v[172:175], v[228:231], v[32:47]
	v_mfma_f32_32x32x16_bf16 v[32:47], v[168:171], v[232:235], v[32:47]
	s_waitcnt lgkmcnt(0)
	v_mfma_f32_32x32x16_bf16 v[0:15], v[180:183], v[184:187], v[0:15]
	v_mfma_f32_32x32x16_bf16 v[0:15], v[176:179], v[188:191], v[0:15]
	v_mfma_f32_32x32x16_bf16 v[0:15], v[172:175], v[192:195], v[0:15]
	v_mfma_f32_32x32x16_bf16 v[0:15], v[168:171], v[196:199], v[0:15]
	v_mfma_f32_32x32x16_bf16 v[16:31], v[180:183], v[164:167], v[16:31]
	v_mfma_f32_32x32x16_bf16 v[16:31], v[176:179], v[160:163], v[16:31]
	v_mfma_f32_32x32x16_bf16 v[16:31], v[172:175], v[156:159], v[16:31]
	v_mfma_f32_32x32x16_bf16 v[16:31], v[168:171], v[152:155], v[16:31]
.Ld3_be_nopv:
	s_waitcnt lgkmcnt(0)
	s_and_b32 s0, s51, 0xc000
	v_add_u32_e32 v240, s0, v217
	ds_read_b64_tr_b16 v[164:165], v240 offset:0
	ds_read_b64_tr_b16 v[166:167], v240 offset:0x800
	ds_read_b64_tr_b16 v[160:161], v240 offset:0x1000
	ds_read_b64_tr_b16 v[162:163], v240 offset:0x1800
	ds_read_b64_tr_b16 v[156:157], v240 offset:0x2000
	ds_read_b64_tr_b16 v[158:159], v240 offset:0x2800
	ds_read_b64_tr_b16 v[152:153], v240 offset:0x3000
	ds_read_b64_tr_b16 v[154:155], v240 offset:0x3800
	s_mov_b64 s[0:1], s[60:61]
	s_barrier
	v_max3_f32 v168, v96, v97, v98
	v_max3_f32 v169, v81, v82, v83
	v_max3_f32 v168, v168, v99, v100
	v_max3_f32 v169, v169, v84, v85
	v_max3_f32 v168, v168, v101, v102
	v_max3_f32 v169, v169, v86, v87
	v_max3_f32 v168, v168, v103, v104
	v_max3_f32 v169, v169, v88, v89
	v_max3_f32 v168, v168, v105, v106
	v_max3_f32 v169, v169, v90, v91
	v_max3_f32 v168, v168, v107, v108
	v_max3_f32 v169, v169, v92, v93
	v_max3_f32 v168, v168, v109, v110
	v_max3_f32 v169, v169, v94, v95
	v_max3_f32 v168, v168, v111, v80
	v_max_f32_e32 v168, v168, v169
	v_mov_b32_e32 v169, v168
	s_nop 1
	v_permlane32_swap_b32_e32 v168, v169
	v_max_f32_e32 v168, v168, v169
	v_cmp_ge_f32_e32 vcc, s83, v168
	v_mov_b32_e32 v184, 1.0
	s_cmp_lg_u64 s[0:1], 0
	s_cbranch_scc1 .Lvt31_first
	s_cmp_lg_u64 vcc, exec
	s_cbranch_scc1 .Lvt31_rare
	s_branch .LBB0_1193

; __device__ __forceinline__ float max3f(float a, float b, float c) { return __builtin_fmaxf(__builtin_fmaxf(a, b), c); }
; __device__ __forceinline__ void rowmax_adjust(f32x16& p0, f32x16& p1, float& m2, f32x16& negm, float& alpha, const bool first) {
;     constexpr float THR2 = THR * 1.4426950408889634f;
;     float pmax = max3f(p0[0], p0[1], p0[2]);
; #pragma unroll
;     for (int r = 3; r < 15; r += 2) pmax = max3f(pmax, p0[r], p0[r + 1]);
;     pmax = max3f(pmax, p0[15], p1[0]);
; #pragma unroll
;     for (int r = 1; r < 15; r += 2) pmax = max3f(pmax, p1[r], p1[r + 1]);
;     pmax = fmaxf(pmax, p1[15]);
;     { auto rr = __builtin_amdgcn_permlane32_swap(__float_as_uint(pmax), __float_as_uint(pmax), false, false);
;       pmax = fmaxf(__uint_as_float(rr[0]), __uint_as_float(rr[1])); }
;     if (!first && __builtin_expect(__all(pmax <= THR2), 1)) { alpha = 1.f; }
.LBB0_1195:
	s_min_u32 s0, s64, 0x7f
	s_lshl_b32 s0, s0, 16
	s_add_i32 s16, s0, 0x40000
	s_add_u32 s0, s58, s16
	s_addc_u32 s1, s59, 0
	global_load_dwordx4 v[132:135], v200, s[0:1]
	global_load_dwordx4 v[128:131], v202, s[0:1]
	v_lshl_add_u64 v[80:81], v[204:205], 0, s[16:17]
	global_load_dwordx4 v[136:139], v[80:81], off
	s_waitcnt lgkmcnt(0)
	s_barrier
	s_or_b32 s0, s64, 1
	s_and_b32 s1, s0, 0xff
	s_mulk_i32 s1, 0xab
	s_bfe_u32 s1, s1, 0x70009
	s_mul_i32 s1, s1, 3
	s_sub_i32 s0, s0, s1
	s_and_b32 s0, s0, 0xff
	s_mulk_i32 s0, 0x2400
	v_add_u32_e32 v84, s0, v218
	s_and_b32 s0, s51, 0x8000
	v_add_u32_e32 v187, s0, v217
	ds_read_b128 v[80:83], v84
	ds_read_b128 v[192:195], v84 offset:4608
	ds_read_b128 v[188:191], v84 offset:32
	ds_read_b128 v[196:199], v84 offset:4640
	ds_read_b128 v[220:223], v84 offset:64
	ds_read_b128 v[228:231], v84 offset:4672
	ds_read_b128 v[224:227], v84 offset:96
	ds_read_b128 v[232:235], v84 offset:4704
	v_mfma_f32_32x32x16_bf16 v[48:63], v[180:183], v[164:167], v[48:63]
	v_mfma_f32_32x32x16_bf16 v[48:63], v[176:179], v[160:163], v[48:63]
	v_mfma_f32_32x32x16_bf16 v[48:63], v[172:175], v[156:159], v[48:63]
	v_mfma_f32_32x32x16_bf16 v[48:63], v[168:171], v[152:155], v[48:63]
	s_waitcnt lgkmcnt(7)
	v_mfma_f32_32x32x16_bf16 v[96:111], v[80:83], v[112:115], v[64:79]
	s_waitcnt lgkmcnt(6)
	v_mfma_f32_32x32x16_bf16 v[80:95], v[192:195], v[112:115], v[64:79]
	s_waitcnt lgkmcnt(5)
	v_mfma_f32_32x32x16_bf16 v[96:111], v[188:191], v[116:119], v[96:111]
	s_waitcnt lgkmcnt(4)
	v_mfma_f32_32x32x16_bf16 v[80:95], v[196:199], v[116:119], v[80:95]
	s_waitcnt lgkmcnt(0)
	ds_read_b64_tr_b16 v[188:189], v187 offset:0x200
	ds_read_b64_tr_b16 v[190:191], v187 offset:0xa00
	ds_read_b64_tr_b16 v[192:193], v187 offset:0x1200
	ds_read_b64_tr_b16 v[194:195], v187 offset:0x1a00
	ds_read_b64_tr_b16 v[196:197], v187 offset:0x2200
	ds_read_b64_tr_b16 v[198:199], v187 offset:0x2a00
	ds_read_b64_tr_b16 v[236:237], v187 offset:0x3200
	ds_read_b64_tr_b16 v[238:239], v187 offset:0x3a00
	ds_read_b64_tr_b16 v[164:165], v187 offset:0x400
	ds_read_b64_tr_b16 v[166:167], v187 offset:0xc00
	ds_read_b64_tr_b16 v[160:161], v187 offset:0x1400
	ds_read_b64_tr_b16 v[162:163], v187 offset:0x1c00
	ds_read_b64_tr_b16 v[156:157], v187 offset:0x2400
	ds_read_b64_tr_b16 v[158:159], v187 offset:0x2c00
	ds_read_b64_tr_b16 v[152:153], v187 offset:0x3400
	ds_read_b64_tr_b16 v[154:155], v187 offset:0x3c00
	v_mfma_f32_32x32x16_bf16 v[96:111], v[220:223], v[120:123], v[96:111]
	v_mfma_f32_32x32x16_bf16 v[80:95], v[228:231], v[120:123], v[80:95]
	v_mfma_f32_32x32x16_bf16 v[96:111], v[224:227], v[124:127], v[96:111]
	v_mfma_f32_32x32x16_bf16 v[80:95], v[232:235], v[124:127], v[80:95]
	ds_read_b64_tr_b16 v[220:221], v187 offset:0x600
	ds_read_b64_tr_b16 v[222:223], v187 offset:0xe00
	ds_read_b64_tr_b16 v[224:225], v187 offset:0x1600
	ds_read_b64_tr_b16 v[226:227], v187 offset:0x1e00
	ds_read_b64_tr_b16 v[228:229], v187 offset:0x2600
	ds_read_b64_tr_b16 v[230:231], v187 offset:0x2e00
	ds_read_b64_tr_b16 v[232:233], v187 offset:0x3600
	ds_read_b64_tr_b16 v[234:235], v187 offset:0x3e00
	s_waitcnt lgkmcnt(15)
	v_mfma_f32_32x32x16_bf16 v[32:47], v[180:183], v[188:191], v[32:47]
	v_mfma_f32_32x32x16_bf16 v[32:47], v[176:179], v[192:195], v[32:47]
	v_mfma_f32_32x32x16_bf16 v[32:47], v[172:175], v[196:199], v[32:47]
	v_mfma_f32_32x32x16_bf16 v[32:47], v[168:171], v[236:239], v[32:47]
	s_waitcnt lgkmcnt(0)
	v_mfma_f32_32x32x16_bf16 v[0:15], v[180:183], v[220:223], v[0:15]
	v_mfma_f32_32x32x16_bf16 v[0:15], v[176:179], v[224:227], v[0:15]
	v_mfma_f32_32x32x16_bf16 v[0:15], v[172:175], v[228:231], v[0:15]
	v_mfma_f32_32x32x16_bf16 v[0:15], v[168:171], v[232:235], v[0:15]
	v_mfma_f32_32x32x16_bf16 v[16:31], v[180:183], v[164:167], v[16:31]
	v_mfma_f32_32x32x16_bf16 v[16:31], v[176:179], v[160:163], v[16:31]
	v_mfma_f32_32x32x16_bf16 v[16:31], v[172:175], v[156:159], v[16:31]
	v_mfma_f32_32x32x16_bf16 v[16:31], v[168:171], v[152:155], v[16:31]
	s_add_i32 s0, s51, 0x4000
	s_and_b32 s0, s0, 0xc000
	v_add_u32_e32 v240, s0, v217
	ds_read_b64_tr_b16 v[164:165], v240 offset:0
	ds_read_b64_tr_b16 v[166:167], v240 offset:0x800
	ds_read_b64_tr_b16 v[160:161], v240 offset:0x1000
	ds_read_b64_tr_b16 v[162:163], v240 offset:0x1800
	ds_read_b64_tr_b16 v[156:157], v240 offset:0x2000
	ds_read_b64_tr_b16 v[158:159], v240 offset:0x2800
	ds_read_b64_tr_b16 v[152:153], v240 offset:0x3000
	ds_read_b64_tr_b16 v[154:155], v240 offset:0x3800
	s_barrier
	v_max3_f32 v168, v96, v97, v98
	v_max3_f32 v169, v81, v82, v83
	v_max3_f32 v168, v168, v99, v100
	v_max3_f32 v169, v169, v84, v85
	v_max3_f32 v168, v168, v101, v102
	v_max3_f32 v169, v169, v86, v87
	v_max3_f32 v168, v168, v103, v104
	v_max3_f32 v169, v169, v88, v89
	v_max3_f32 v168, v168, v105, v106
	v_max3_f32 v169, v169, v90, v91
	v_max3_f32 v168, v168, v107, v108
	v_max3_f32 v169, v169, v92, v93
	v_max3_f32 v168, v168, v109, v110
	v_max3_f32 v169, v169, v94, v95
	v_max3_f32 v168, v168, v111, v80
	v_max_f32_e32 v168, v168, v169
	v_mov_b32_e32 v169, v168
	s_nop 1
	v_permlane32_swap_b32_e32 v168, v169
	v_max_f32_e32 v168, v168, v169
	v_cmp_ge_f32_e32 vcc, s83, v168
	v_mov_b32_e32 v187, 1.0
	s_cmp_eq_u64 vcc, exec
	s_cbranch_scc1 .LBB0_1200
	s_branch .LBB0_1202
